# as v034 plus: workgroup 0 clears the barrier ready flag at kernel exit (robust against a non-repoisoned workspace)
# speedup vs baseline: 1.0167x; 1.0006x over previous
.Lfin_flag:
	v_readlane_b32 s0, v254, 21
	s_nop 3
	s_cmp_lg_u32 s0, 0
	s_cbranch_scc1 .LBB0_871
	v_cmp_eq_u32_e32 vcc, 0, v173
	s_and_saveexec_b64 s[0:1], vcc
	s_cbranch_execz .LBB0_871
	v_readlane_b32 s4, v252, 4
	v_readlane_b32 s5, v252, 5
	s_nop 3
	s_add_u32 s4, s4, 0x3c00
	s_addc_u32 s5, s5, 0
	v_mov_b32_e32 v0, 0
	s_nop 1
	global_store_dword v0, v0, s[4:5] sc0 sc1
